# P7 epilogue: all gate/TMP loads issued up front; K1 W_in transpose: 16 loads in flight instead of 1
# speedup vs baseline: 1.0126x; 1.0126x over previous
.LBB0_34:
	v_mov_b32_e32 v100, 0
	v_mov_b32_e32 v101, 0
	v_mov_b32_e32 v102, 0
	v_mov_b32_e32 v103, 0
	v_mov_b32_e32 v104, 0
	v_mov_b32_e32 v105, 0
	v_mov_b32_e32 v106, 0
	v_mov_b32_e32 v107, 0
	s_and_saveexec_b64 s[24:25], s[18:19]
	s_cbranch_execz .Lk1_skipw
	v_lshl_add_u64 v[116:117], v[34:35], 0, s[22:23]
	global_load_dword v100, v[116:117], off
	v_lshl_add_u64 v[118:119], v[30:31], 0, s[22:23]
	global_load_dword v101, v[118:119], off
	v_lshl_add_u64 v[116:117], v[28:29], 0, s[22:23]
	global_load_dword v102, v[116:117], off
	v_lshl_add_u64 v[118:119], v[26:27], 0, s[22:23]
	global_load_dword v103, v[118:119], off
	v_lshl_add_u64 v[116:117], v[24:25], 0, s[22:23]
	global_load_dword v104, v[116:117], off
	v_lshl_add_u64 v[118:119], v[22:23], 0, s[22:23]
	global_load_dword v105, v[118:119], off
	v_lshl_add_u64 v[116:117], v[20:21], 0, s[22:23]
	global_load_dword v106, v[116:117], off
	v_lshl_add_u64 v[118:119], v[16:17], 0, s[22:23]
	global_load_dword v107, v[118:119], off
.Lk1_skipw:
	s_or_b64 exec, exec, s[24:25]
	s_andn2_b64 vcc, exec, s[12:13]
	s_cbranch_vccnz .Lk1_nokscale
	v_lshl_add_u64 v[116:117], v[32:33], 0, s[20:21]
	global_load_dword v108, v[116:117], off
	v_lshl_add_u64 v[118:119], v[18:19], 0, s[20:21]
	global_load_dword v109, v[118:119], off offset:8
	global_load_dword v110, v[118:119], off offset:16
	global_load_dword v111, v[118:119], off offset:24
	global_load_dword v112, v[118:119], off offset:32
	global_load_dword v113, v[118:119], off offset:40
	global_load_dword v114, v[118:119], off offset:48
	global_load_dword v115, v[118:119], off offset:56
	s_waitcnt vmcnt(0)
	v_mul_f32_e32 v100, v100, v108
	v_mul_f32_e32 v101, v101, v109
	v_mul_f32_e32 v102, v102, v110
	v_mul_f32_e32 v103, v103, v111
	v_mul_f32_e32 v104, v104, v112
	v_mul_f32_e32 v105, v105, v113
	v_mul_f32_e32 v106, v106, v114
	v_mul_f32_e32 v107, v107, v115
.Lk1_nokscale:
	s_waitcnt vmcnt(0)
	ds_write_b32 v6, v100
	ds_write_b32 v6, v101 offset:264
	ds_write_b32 v6, v102 offset:528
	ds_write_b32 v6, v103 offset:792
	ds_write_b32 v6, v104 offset:1056
	ds_write_b32 v6, v105 offset:1320
	ds_write_b32 v6, v106 offset:1584
	ds_write_b32 v6, v107 offset:1848
	s_add_u32 s22, s22, 0x7c300
	s_addc_u32 s23, s23, 0
	v_add_u32_e32 v6, 0x840, v6
	v_lshl_add_u64 v[18:19], v[18:19], 0, 64
	v_lshl_add_u64 v[32:33], v[32:33], 0, 64
	s_cmp_lg_u32 s22, 0x1f0c00
	s_cbranch_scc1 .LBB0_34
	s_branch .LBB0_7

.LBB0_842:
	s_lshl_b32 s0, s43, 11
	s_ashr_i32 s1, s0, 31
	v_readlane_b32 s3, v253, 3
	s_add_u32 s0, s3, s0
	v_readlane_b32 s3, v253, 4
	s_addc_u32 s1, s3, s1
	s_lshl_b32 s45, s40, 8
	v_lshl_or_b32 v152, s42, 7, v181
	v_add_u32_e32 v156, s45, v176
	v_ashrrev_i32_e32 v153, 31, v152
	v_ashrrev_i32_e32 v157, 31, v156
	v_lshl_add_u64 v[154:155], s[0:1], 0, v[152:153]
	v_lshlrev_b64 v[66:67], 12, v[156:157]
	v_lshl_add_u64 v[66:67], v[154:155], 0, v[66:67]
	global_load_dwordx2 v[172:173], v[66:67], off
	global_load_dwordx2 v[174:175], v[66:67], off offset:1024
	v_lshlrev_b32_e32 v208, 12, v156
	v_add_u32_e32 v208, v208, v152
	v_add_u32_e32 v209, 0x10000, v208
	global_load_dwordx2 v[164:165], v209, s[0:1]
	global_load_dwordx2 v[166:167], v209, s[0:1] offset:1024
	v_add_u32_e32 v209, 0x20000, v208
	global_load_dwordx2 v[188:189], v209, s[0:1]
	global_load_dwordx2 v[190:191], v209, s[0:1] offset:1024
	v_add_u32_e32 v209, 0x30000, v208
	global_load_dwordx2 v[192:193], v209, s[0:1]
	global_load_dwordx2 v[194:195], v209, s[0:1] offset:1024
	v_add_u32_e32 v209, 0x80000, v208
	global_load_dwordx2 v[196:197], v209, s[0:1]
	global_load_dwordx2 v[198:199], v209, s[0:1] offset:1024
	v_add_u32_e32 v209, 0x90000, v208
	global_load_dwordx2 v[200:201], v209, s[0:1]
	global_load_dwordx2 v[202:203], v209, s[0:1] offset:1024
	v_add_u32_e32 v209, 0xa0000, v208
	global_load_dwordx2 v[204:205], v209, s[0:1]
	global_load_dwordx2 v[206:207], v209, s[0:1] offset:1024
	v_add_u32_e32 v209, 0xb0000, v208
	global_load_dwordx2 v[226:227], v209, s[0:1]
	global_load_dwordx2 v[228:229], v209, s[0:1] offset:1024
	v_readlane_b32 s0, v252, 1
	v_readlane_b32 s1, v252, 2
	s_mov_b64 s[6:7], s[0:1]
	s_cmp_gt_i32 s43, 0
	v_lshlrev_b64 v[170:171], 11, v[156:157]
	v_lshl_add_u64 v[158:159], v[152:153], 1, s[0:1]
	v_readlane_b32 s10, v254, 21
	s_cselect_b64 s[0:1], -1, 0
	s_cmp_lt_i32 s43, 1
	v_lshl_add_u64 v[168:169], v[158:159], 0, v[170:171]
	v_readlane_b32 s11, v254, 22
	s_cbranch_scc1 .LBB0_844
	global_load_dwordx4 v[136:139], v[168:169], off
	v_lshlrev_b32_e32 v208, 11, v156
	v_lshl_add_u32 v208, v152, 1, v208
	v_add_u32_e32 v209, 0x10000, v208
	global_load_dwordx4 v[216:219], v209, s[6:7]
	v_add_u32_e32 v209, 0x18000, v208
	global_load_dwordx4 v[230:233], v209, s[6:7]
	v_add_u32_e32 v209, 0x40000, v208
	global_load_dwordx4 v[234:237], v209, s[6:7]
	v_add_u32_e32 v209, 0x48000, v208
	global_load_dwordx4 v[238:241], v209, s[6:7]
	v_add_u32_e32 v209, 0x50000, v208
	global_load_dwordx4 v[242:245], v209, s[6:7]
	v_add_u32_e32 v209, 0x58000, v208
	global_load_dwordx4 v[246:249], v209, s[6:7]
	s_branch .LBB0_845

.LBB0_845:
	v_add_u32_e32 v66, s45, v178
	v_ashrrev_i32_e32 v67, 31, v66
	v_lshlrev_b64 v[132:133], 12, v[66:67]
	v_lshl_add_u64 v[132:133], v[154:155], 0, v[132:133]
	s_nop 0
	s_nop 0
	v_cndmask_b32_e64 v64, 0, 1, s[0:1]
	v_lshlrev_b64 v[162:163], 11, v[66:67]
	v_cmp_ne_u32_e64 s[40:41], 1, v64
	s_andn2_b64 vcc, exec, s[0:1]
	v_lshl_add_u64 v[160:161], v[158:159], 0, v[162:163]
	s_cbranch_vccnz .LBB0_847
	global_load_dwordx4 v[132:135], v[160:161], off
	s_branch .LBB0_848

.LBB0_851:
	v_add_u32_e32 v66, s45, v179
	v_ashrrev_i32_e32 v67, 31, v66
	v_lshlrev_b64 v[92:93], 12, v[66:67]
	v_lshl_add_u64 v[92:93], v[154:155], 0, v[92:93]
	s_nop 0
	s_nop 0
	v_lshlrev_b64 v[96:97], 11, v[66:67]
	v_mov_b64_e32 v[92:93], v[132:133]
	s_and_b64 vcc, exec, s[40:41]
	v_lshl_add_u64 v[66:67], v[158:159], 0, v[96:97]
	v_mov_b64_e32 v[94:95], v[134:135]
	s_nop 0
	s_nop 0

.LBB0_856:
	s_nop 1
	v_add_u32_e32 v76, s45, v180
	v_ashrrev_i32_e32 v77, 31, v76
	v_lshlrev_b64 v[78:79], 12, v[76:77]
	v_lshl_add_u64 v[78:79], v[154:155], 0, v[78:79]
	s_nop 0
	s_nop 0
	v_lshlrev_b64 v[82:83], 11, v[76:77]
	s_nop 0
	v_mov_b64_e32 v[76:77], v[92:93]
	s_and_b64 vcc, exec, s[40:41]
	v_lshl_add_u64 v[80:81], v[158:159], 0, v[82:83]
	v_mov_b64_e32 v[78:79], v[94:95]
	s_nop 0
	s_nop 0
.LBB0_858:
	v_lshlrev_b32_e32 v64, 16, v216
	v_and_b32_e32 v120, 0xffff0000, v216
	v_lshlrev_b32_e32 v121, 16, v217
	v_and_b32_e32 v122, 0xffff0000, v217
	v_lshlrev_b32_e32 v123, 16, v218
	v_and_b32_e32 v126, 0xffff0000, v218
	v_lshlrev_b32_e32 v127, 16, v219
	v_and_b32_e32 v128, 0xffff0000, v219
	v_cvt_f32_ubyte0_e32 v93, v190
	v_cvt_f32_ubyte0_e32 v92, v188
	v_mov_b32_e32 v94, v60
	v_mov_b32_e32 v95, v112
	v_pk_mul_f32 v[92:93], v[94:95], v[92:93]
	v_mov_b32_e32 v112, v61
	v_add_f32_e32 v60, v92, v93
	v_mul_f32_e32 v92, 0x3b808081, v60
	v_fmac_f32_e32 v64, 0x3b808081, v60
	v_cndmask_b32_e64 v64, v92, v64, s[0:1]
	v_cvt_f32_ubyte1_e32 v93, v190
	v_cvt_f32_ubyte1_e32 v92, v188
	v_pk_mul_f32 v[60:61], v[112:113], v[92:93]
	v_mov_b32_e32 v92, v62
	v_add_f32_e32 v60, v60, v61
	v_mul_f32_e32 v61, 0x3b808081, v60
	v_fmac_f32_e32 v120, 0x3b808081, v60
	v_cndmask_b32_e64 v94, v61, v120, s[0:1]
	v_cvt_f32_ubyte2_e32 v61, v190
	v_cvt_f32_ubyte2_e32 v60, v188
	v_mov_b32_e32 v93, v114
	v_pk_mul_f32 v[60:61], v[92:93], v[60:61]
	v_mov_b32_e32 v114, v63
	v_add_f32_e32 v60, v60, v61
	v_mul_f32_e32 v61, 0x3b808081, v60
	v_fmac_f32_e32 v121, 0x3b808081, v60
	v_cndmask_b32_e64 v92, v61, v121, s[0:1]
	v_cvt_f32_ubyte3_e32 v61, v190
	v_cvt_f32_ubyte3_e32 v60, v188
	v_pk_mul_f32 v[60:61], v[114:115], v[60:61]
	v_mov_b32_e32 v62, v56
	v_add_f32_e32 v60, v60, v61
	v_mul_f32_e32 v61, 0x3b808081, v60
	v_fmac_f32_e32 v122, 0x3b808081, v60
	v_cndmask_b32_e64 v93, v61, v122, s[0:1]
	v_cvt_f32_ubyte0_e32 v61, v191
	v_cvt_f32_ubyte0_e32 v60, v189
	v_mov_b32_e32 v63, v108
	v_pk_mul_f32 v[60:61], v[62:63], v[60:61]
	v_mov_b32_e32 v108, v57
	v_add_f32_e32 v56, v60, v61
	v_mul_f32_e32 v60, 0x3b808081, v56
	v_fmac_f32_e32 v123, 0x3b808081, v56
	v_cndmask_b32_e64 v62, v60, v123, s[0:1]
	v_cvt_f32_ubyte1_e32 v61, v191
	v_cvt_f32_ubyte1_e32 v60, v189
	v_pk_mul_f32 v[56:57], v[108:109], v[60:61]
	v_mov_b32_e32 v60, v58
	v_add_f32_e32 v56, v56, v57
	v_mul_f32_e32 v57, 0x3b808081, v56
	v_fmac_f32_e32 v126, 0x3b808081, v56
	v_cndmask_b32_e64 v63, v57, v126, s[0:1]
	v_cvt_f32_ubyte2_e32 v57, v191
	v_cvt_f32_ubyte2_e32 v56, v189
	v_mov_b32_e32 v61, v110
	v_pk_mul_f32 v[56:57], v[60:61], v[56:57]
	v_mov_b32_e32 v110, v59
	v_add_f32_e32 v56, v56, v57
	v_mul_f32_e32 v57, 0x3b808081, v56
	v_fmac_f32_e32 v127, 0x3b808081, v56
	v_cndmask_b32_e64 v60, v57, v127, s[0:1]
	v_cvt_f32_ubyte3_e32 v57, v191
	v_cvt_f32_ubyte3_e32 v56, v189
	v_pk_mul_f32 v[56:57], v[110:111], v[56:57]
	v_cvt_pk_bf16_f32 v58, v62, v63
	v_add_f32_e32 v56, v56, v57
	v_mul_f32_e32 v57, 0x3b808081, v56
	v_fmac_f32_e32 v128, 0x3b808081, v56
	v_cndmask_b32_e64 v59, v57, v128, s[0:1]
	v_cvt_pk_bf16_f32 v56, v64, v94
	v_cvt_pk_bf16_f32 v57, v92, v93
	s_and_b64 vcc, exec, s[42:43]
	v_cvt_pk_bf16_f32 v59, v60, v59
	s_cbranch_vccnz .LBB0_889
	v_lshl_add_u64 v[60:61], s[10:11], 0, v[96:97]
	v_lshl_add_u64 v[60:61], v[152:153], 1, v[60:61]
	global_store_dwordx4 v[60:61], v[56:59], off
	s_cbranch_execnz .LBB0_861

.LBB0_861:
	s_nop 1
	v_add_u32_e32 v56, 0x80, v156
	v_ashrrev_i32_e32 v57, 31, v56
	v_lshlrev_b64 v[58:59], 12, v[56:57]
	v_lshl_add_u64 v[58:59], v[154:155], 0, v[58:59]
	s_nop 0
	s_nop 0
	v_lshlrev_b64 v[62:63], 11, v[56:57]
	s_nop 0
	v_mov_b64_e32 v[56:57], v[76:77]
	s_and_b64 vcc, exec, s[40:41]
	v_lshl_add_u64 v[60:61], v[158:159], 0, v[62:63]
	v_mov_b64_e32 v[58:59], v[78:79]
	s_nop 0
	s_nop 0
.LBB0_863:
	v_lshlrev_b32_e32 v64, 16, v230
	v_and_b32_e32 v94, 0xffff0000, v230
	v_lshlrev_b32_e32 v95, 16, v231
	v_and_b32_e32 v96, 0xffff0000, v231
	v_lshlrev_b32_e32 v97, 16, v232
	v_and_b32_e32 v98, 0xffff0000, v232
	v_lshlrev_b32_e32 v99, 16, v233
	v_and_b32_e32 v108, 0xffff0000, v233
	v_cvt_f32_ubyte0_e32 v77, v194
	v_cvt_f32_ubyte0_e32 v76, v192
	v_mov_b32_e32 v78, v44
	v_mov_b32_e32 v79, v104
	v_pk_mul_f32 v[76:77], v[78:79], v[76:77]
	v_mov_b32_e32 v104, v45
	v_add_f32_e32 v44, v76, v77
	v_mul_f32_e32 v76, 0x3b808081, v44
	v_fmac_f32_e32 v64, 0x3b808081, v44
	v_cndmask_b32_e64 v64, v76, v64, s[0:1]
	v_cvt_f32_ubyte1_e32 v77, v194
	v_cvt_f32_ubyte1_e32 v76, v192
	v_pk_mul_f32 v[44:45], v[104:105], v[76:77]
	v_mov_b32_e32 v76, v46
	v_add_f32_e32 v44, v44, v45
	v_mul_f32_e32 v45, 0x3b808081, v44
	v_fmac_f32_e32 v94, 0x3b808081, v44
	v_cndmask_b32_e64 v78, v45, v94, s[0:1]
	v_cvt_f32_ubyte2_e32 v45, v194
	v_cvt_f32_ubyte2_e32 v44, v192
	v_mov_b32_e32 v77, v106
	v_pk_mul_f32 v[44:45], v[76:77], v[44:45]
	v_mov_b32_e32 v106, v47
	v_add_f32_e32 v44, v44, v45
	v_mul_f32_e32 v45, 0x3b808081, v44
	v_fmac_f32_e32 v95, 0x3b808081, v44
	v_cndmask_b32_e64 v76, v45, v95, s[0:1]
	v_cvt_f32_ubyte3_e32 v45, v194
	v_cvt_f32_ubyte3_e32 v44, v192
	v_pk_mul_f32 v[44:45], v[106:107], v[44:45]
	v_mov_b32_e32 v46, v40
	v_add_f32_e32 v44, v44, v45
	v_mul_f32_e32 v45, 0x3b808081, v44
	v_fmac_f32_e32 v96, 0x3b808081, v44
	v_cndmask_b32_e64 v77, v45, v96, s[0:1]
	v_cvt_f32_ubyte0_e32 v45, v195
	v_cvt_f32_ubyte0_e32 v44, v193
	v_mov_b32_e32 v47, v100
	v_pk_mul_f32 v[44:45], v[46:47], v[44:45]
	v_mov_b32_e32 v100, v41
	v_add_f32_e32 v40, v44, v45
	v_mul_f32_e32 v44, 0x3b808081, v40
	v_fmac_f32_e32 v97, 0x3b808081, v40
	v_cndmask_b32_e64 v46, v44, v97, s[0:1]
	v_cvt_f32_ubyte1_e32 v45, v195
	v_cvt_f32_ubyte1_e32 v44, v193
	v_pk_mul_f32 v[40:41], v[100:101], v[44:45]
	v_mov_b32_e32 v44, v42
	v_add_f32_e32 v40, v40, v41
	v_mul_f32_e32 v41, 0x3b808081, v40
	v_fmac_f32_e32 v98, 0x3b808081, v40
	v_cndmask_b32_e64 v47, v41, v98, s[0:1]
	v_cvt_f32_ubyte2_e32 v41, v195
	v_cvt_f32_ubyte2_e32 v40, v193
	v_mov_b32_e32 v45, v102
	v_pk_mul_f32 v[40:41], v[44:45], v[40:41]
	v_mov_b32_e32 v102, v43
	v_add_f32_e32 v40, v40, v41
	v_mul_f32_e32 v41, 0x3b808081, v40
	v_fmac_f32_e32 v99, 0x3b808081, v40
	v_cndmask_b32_e64 v44, v41, v99, s[0:1]
	v_cvt_f32_ubyte3_e32 v41, v195
	v_cvt_f32_ubyte3_e32 v40, v193
	v_pk_mul_f32 v[40:41], v[102:103], v[40:41]
	v_cvt_pk_bf16_f32 v42, v46, v47
	v_add_f32_e32 v40, v40, v41
	v_mul_f32_e32 v41, 0x3b808081, v40
	v_fmac_f32_e32 v108, 0x3b808081, v40
	v_cndmask_b32_e64 v43, v41, v108, s[0:1]
	v_cvt_pk_bf16_f32 v40, v64, v78
	v_cvt_pk_bf16_f32 v41, v76, v77
	s_and_b64 vcc, exec, s[42:43]
	v_cvt_pk_bf16_f32 v43, v44, v43
	s_cbranch_vccnz .LBB0_890
	v_lshl_add_u64 v[44:45], s[10:11], 0, v[82:83]
	v_lshl_add_u64 v[44:45], v[152:153], 1, v[44:45]
	global_store_dwordx4 v[44:45], v[40:43], off
	s_cbranch_execnz .LBB0_866

.LBB0_866:
	s_nop 1
	v_add_u32_e32 v40, 0x90, v156
	v_ashrrev_i32_e32 v41, 31, v40
	v_lshlrev_b64 v[42:43], 12, v[40:41]
	v_lshl_add_u64 v[42:43], v[154:155], 0, v[42:43]
	s_nop 0
	s_nop 0
	v_lshlrev_b64 v[46:47], 11, v[40:41]
	s_nop 0
	v_mov_b64_e32 v[40:41], v[56:57]
	s_and_b64 vcc, exec, s[40:41]
	v_lshl_add_u64 v[44:45], v[158:159], 0, v[46:47]
	v_mov_b64_e32 v[42:43], v[58:59]
	s_nop 0
	s_nop 0
.LBB0_868:
	v_lshlrev_b32_e32 v64, 16, v234
	v_and_b32_e32 v80, 0xffff0000, v234
	v_lshlrev_b32_e32 v81, 16, v235
	v_and_b32_e32 v82, 0xffff0000, v235
	v_lshlrev_b32_e32 v83, 16, v236
	v_and_b32_e32 v94, 0xffff0000, v236
	v_lshlrev_b32_e32 v95, 16, v237
	v_and_b32_e32 v96, 0xffff0000, v237
	v_cvt_f32_ubyte0_e32 v57, v198
	v_cvt_f32_ubyte0_e32 v56, v196
	v_mov_b32_e32 v58, v28
	v_mov_b32_e32 v59, v88
	v_pk_mul_f32 v[56:57], v[58:59], v[56:57]
	v_mov_b32_e32 v88, v29
	v_add_f32_e32 v28, v56, v57
	v_mul_f32_e32 v56, 0x3b808081, v28
	v_fmac_f32_e32 v64, 0x3b808081, v28
	v_cndmask_b32_e64 v58, v56, v64, s[0:1]
	v_cvt_f32_ubyte1_e32 v57, v198
	v_cvt_f32_ubyte1_e32 v56, v196
	v_pk_mul_f32 v[28:29], v[88:89], v[56:57]
	v_mov_b32_e32 v56, v30
	v_add_f32_e32 v28, v28, v29
	v_mul_f32_e32 v29, 0x3b808081, v28
	v_fmac_f32_e32 v80, 0x3b808081, v28
	v_cndmask_b32_e64 v59, v29, v80, s[0:1]
	v_cvt_f32_ubyte2_e32 v29, v198
	v_cvt_f32_ubyte2_e32 v28, v196
	v_mov_b32_e32 v57, v90
	v_pk_mul_f32 v[28:29], v[56:57], v[28:29]
	v_mov_b32_e32 v90, v31
	v_add_f32_e32 v28, v28, v29
	v_mul_f32_e32 v29, 0x3b808081, v28
	v_fmac_f32_e32 v81, 0x3b808081, v28
	v_cndmask_b32_e64 v56, v29, v81, s[0:1]
	v_cvt_f32_ubyte3_e32 v29, v198
	v_cvt_f32_ubyte3_e32 v28, v196
	v_pk_mul_f32 v[28:29], v[90:91], v[28:29]
	v_mov_b32_e32 v30, v24
	v_add_f32_e32 v28, v28, v29
	v_mul_f32_e32 v29, 0x3b808081, v28
	v_fmac_f32_e32 v82, 0x3b808081, v28
	v_cndmask_b32_e64 v57, v29, v82, s[0:1]
	v_cvt_f32_ubyte0_e32 v29, v199
	v_cvt_f32_ubyte0_e32 v28, v197
	v_mov_b32_e32 v31, v84
	v_pk_mul_f32 v[28:29], v[30:31], v[28:29]
	v_mov_b32_e32 v84, v25
	v_add_f32_e32 v24, v28, v29
	v_mul_f32_e32 v28, 0x3b808081, v24
	v_fmac_f32_e32 v83, 0x3b808081, v24
	v_cndmask_b32_e64 v30, v28, v83, s[0:1]
	v_cvt_f32_ubyte1_e32 v29, v199
	v_cvt_f32_ubyte1_e32 v28, v197
	v_pk_mul_f32 v[24:25], v[84:85], v[28:29]
	v_mov_b32_e32 v28, v26
	v_add_f32_e32 v24, v24, v25
	v_mul_f32_e32 v25, 0x3b808081, v24
	v_fmac_f32_e32 v94, 0x3b808081, v24
	v_cndmask_b32_e64 v31, v25, v94, s[0:1]
	v_cvt_f32_ubyte2_e32 v25, v199
	v_cvt_f32_ubyte2_e32 v24, v197
	v_mov_b32_e32 v29, v86
	v_pk_mul_f32 v[24:25], v[28:29], v[24:25]
	v_mov_b32_e32 v86, v27
	v_add_f32_e32 v24, v24, v25
	v_mul_f32_e32 v25, 0x3b808081, v24
	v_fmac_f32_e32 v95, 0x3b808081, v24
	v_cndmask_b32_e64 v28, v25, v95, s[0:1]
	v_cvt_f32_ubyte3_e32 v25, v199
	v_cvt_f32_ubyte3_e32 v24, v197
	v_pk_mul_f32 v[24:25], v[86:87], v[24:25]
	v_cvt_pk_bf16_f32 v26, v30, v31
	v_add_f32_e32 v24, v24, v25
	v_mul_f32_e32 v25, 0x3b808081, v24
	v_fmac_f32_e32 v96, 0x3b808081, v24
	v_cndmask_b32_e64 v27, v25, v96, s[0:1]
	v_cvt_pk_bf16_f32 v24, v58, v59
	v_cvt_pk_bf16_f32 v25, v56, v57
	s_and_b64 vcc, exec, s[42:43]
	v_cvt_pk_bf16_f32 v27, v28, v27
	s_cbranch_vccnz .LBB0_891
	v_lshl_add_u64 v[28:29], s[10:11], 0, v[62:63]
	v_lshl_add_u64 v[28:29], v[152:153], 1, v[28:29]
	global_store_dwordx4 v[28:29], v[24:27], off
	s_cbranch_execnz .LBB0_871

.LBB0_871:
	s_nop 1
	v_add_u32_e32 v24, 0xa0, v156
	v_ashrrev_i32_e32 v25, 31, v24
	v_lshlrev_b64 v[26:27], 12, v[24:25]
	v_lshl_add_u64 v[26:27], v[154:155], 0, v[26:27]
	s_nop 0
	s_nop 0
	v_lshlrev_b64 v[30:31], 11, v[24:25]
	s_nop 0
	v_mov_b64_e32 v[24:25], v[40:41]
	s_and_b64 vcc, exec, s[40:41]
	v_lshl_add_u64 v[28:29], v[158:159], 0, v[30:31]
	v_mov_b64_e32 v[26:27], v[42:43]
	s_nop 0
	s_nop 0
.LBB0_873:
	v_lshlrev_b32_e32 v60, 16, v238
	v_and_b32_e32 v61, 0xffff0000, v238
	v_lshlrev_b32_e32 v62, 16, v239
	v_and_b32_e32 v63, 0xffff0000, v239
	v_lshlrev_b32_e32 v64, 16, v240
	v_and_b32_e32 v66, 0xffff0000, v240
	v_lshlrev_b32_e32 v67, 16, v241
	v_and_b32_e32 v80, 0xffff0000, v241
	v_cvt_f32_ubyte0_e32 v41, v202
	v_cvt_f32_ubyte0_e32 v40, v200
	v_mov_b32_e32 v42, v20
	v_mov_b32_e32 v43, v72
	v_pk_mul_f32 v[40:41], v[42:43], v[40:41]
	v_mov_b32_e32 v72, v21
	v_add_f32_e32 v20, v40, v41
	v_mul_f32_e32 v40, 0x3b808081, v20
	v_fmac_f32_e32 v60, 0x3b808081, v20
	v_cndmask_b32_e64 v42, v40, v60, s[0:1]
	v_cvt_f32_ubyte1_e32 v41, v202
	v_cvt_f32_ubyte1_e32 v40, v200
	v_pk_mul_f32 v[20:21], v[72:73], v[40:41]
	v_mov_b32_e32 v40, v22
	v_add_f32_e32 v20, v20, v21
	v_mul_f32_e32 v21, 0x3b808081, v20
	v_fmac_f32_e32 v61, 0x3b808081, v20
	v_cndmask_b32_e64 v43, v21, v61, s[0:1]
	v_cvt_f32_ubyte2_e32 v21, v202
	v_cvt_f32_ubyte2_e32 v20, v200
	v_mov_b32_e32 v41, v74
	v_pk_mul_f32 v[20:21], v[40:41], v[20:21]
	v_mov_b32_e32 v74, v23
	v_add_f32_e32 v20, v20, v21
	v_mul_f32_e32 v21, 0x3b808081, v20
	v_fmac_f32_e32 v62, 0x3b808081, v20
	v_cndmask_b32_e64 v40, v21, v62, s[0:1]
	v_cvt_f32_ubyte3_e32 v21, v202
	v_cvt_f32_ubyte3_e32 v20, v200
	v_pk_mul_f32 v[20:21], v[74:75], v[20:21]
	v_mov_b32_e32 v22, v16
	v_add_f32_e32 v20, v20, v21
	v_mul_f32_e32 v21, 0x3b808081, v20
	v_fmac_f32_e32 v63, 0x3b808081, v20
	v_cndmask_b32_e64 v41, v21, v63, s[0:1]
	v_cvt_f32_ubyte0_e32 v21, v203
	v_cvt_f32_ubyte0_e32 v20, v201
	v_mov_b32_e32 v23, v68
	v_pk_mul_f32 v[20:21], v[22:23], v[20:21]
	v_mov_b32_e32 v68, v17
	v_add_f32_e32 v16, v20, v21
	v_mul_f32_e32 v20, 0x3b808081, v16
	v_fmac_f32_e32 v64, 0x3b808081, v16
	v_cndmask_b32_e64 v22, v20, v64, s[0:1]
	v_cvt_f32_ubyte1_e32 v21, v203
	v_cvt_f32_ubyte1_e32 v20, v201
	v_pk_mul_f32 v[16:17], v[68:69], v[20:21]
	v_mov_b32_e32 v20, v18
	v_add_f32_e32 v16, v16, v17
	v_mul_f32_e32 v17, 0x3b808081, v16
	v_fmac_f32_e32 v66, 0x3b808081, v16
	v_cndmask_b32_e64 v23, v17, v66, s[0:1]
	v_cvt_f32_ubyte2_e32 v17, v203
	v_cvt_f32_ubyte2_e32 v16, v201
	v_mov_b32_e32 v21, v70
	v_pk_mul_f32 v[16:17], v[20:21], v[16:17]
	v_mov_b32_e32 v70, v19
	v_add_f32_e32 v16, v16, v17
	v_mul_f32_e32 v17, 0x3b808081, v16
	v_fmac_f32_e32 v67, 0x3b808081, v16
	v_cndmask_b32_e64 v20, v17, v67, s[0:1]
	v_cvt_f32_ubyte3_e32 v17, v203
	v_cvt_f32_ubyte3_e32 v16, v201
	v_pk_mul_f32 v[16:17], v[70:71], v[16:17]
	v_cvt_pk_bf16_f32 v18, v22, v23
	v_add_f32_e32 v16, v16, v17
	v_mul_f32_e32 v17, 0x3b808081, v16
	v_fmac_f32_e32 v80, 0x3b808081, v16
	v_cndmask_b32_e64 v19, v17, v80, s[0:1]
	v_cvt_pk_bf16_f32 v16, v42, v43
	v_cvt_pk_bf16_f32 v17, v40, v41
	s_and_b64 vcc, exec, s[42:43]
	v_cvt_pk_bf16_f32 v19, v20, v19
	s_cbranch_vccnz .LBB0_892
	v_lshl_add_u64 v[20:21], s[10:11], 0, v[46:47]
	v_lshl_add_u64 v[20:21], v[152:153], 1, v[20:21]
	global_store_dwordx4 v[20:21], v[16:19], off
	s_cbranch_execnz .LBB0_876

.LBB0_876:
	s_nop 1
	v_add_u32_e32 v16, 0xb0, v156
	v_ashrrev_i32_e32 v17, 31, v16
	v_lshlrev_b64 v[18:19], 12, v[16:17]
	v_lshl_add_u64 v[18:19], v[154:155], 0, v[18:19]
	s_nop 0
	s_nop 0
	v_lshlrev_b64 v[22:23], 11, v[16:17]
	s_nop 0
	v_mov_b64_e32 v[16:17], v[24:25]
	s_and_b64 vcc, exec, s[40:41]
	v_lshl_add_u64 v[20:21], v[158:159], 0, v[22:23]
	v_mov_b64_e32 v[18:19], v[26:27]
	s_nop 0
	s_nop 0
.LBB0_878:
	v_lshlrev_b32_e32 v44, 16, v242
	v_and_b32_e32 v45, 0xffff0000, v242
	v_lshlrev_b32_e32 v46, 16, v243
	v_and_b32_e32 v47, 0xffff0000, v243
	v_lshlrev_b32_e32 v60, 16, v244
	v_and_b32_e32 v61, 0xffff0000, v244
	v_lshlrev_b32_e32 v62, 16, v245
	v_and_b32_e32 v63, 0xffff0000, v245
	v_cvt_f32_ubyte0_e32 v25, v206
	v_cvt_f32_ubyte0_e32 v24, v204
	v_mov_b32_e32 v26, v12
	v_mov_b32_e32 v27, v52
	v_pk_mul_f32 v[24:25], v[26:27], v[24:25]
	v_mov_b32_e32 v52, v13
	v_add_f32_e32 v12, v24, v25
	v_mul_f32_e32 v24, 0x3b808081, v12
	v_fmac_f32_e32 v44, 0x3b808081, v12
	v_cndmask_b32_e64 v26, v24, v44, s[0:1]
	v_cvt_f32_ubyte1_e32 v25, v206
	v_cvt_f32_ubyte1_e32 v24, v204
	v_pk_mul_f32 v[12:13], v[52:53], v[24:25]
	v_mov_b32_e32 v24, v14
	v_add_f32_e32 v12, v12, v13
	v_mul_f32_e32 v13, 0x3b808081, v12
	v_fmac_f32_e32 v45, 0x3b808081, v12
	v_cndmask_b32_e64 v27, v13, v45, s[0:1]
	v_cvt_f32_ubyte2_e32 v13, v206
	v_cvt_f32_ubyte2_e32 v12, v204
	v_mov_b32_e32 v25, v54
	v_pk_mul_f32 v[12:13], v[24:25], v[12:13]
	v_mov_b32_e32 v54, v15
	v_add_f32_e32 v12, v12, v13
	v_mul_f32_e32 v13, 0x3b808081, v12
	v_fmac_f32_e32 v46, 0x3b808081, v12
	v_cndmask_b32_e64 v24, v13, v46, s[0:1]
	v_cvt_f32_ubyte3_e32 v13, v206
	v_cvt_f32_ubyte3_e32 v12, v204
	v_pk_mul_f32 v[12:13], v[54:55], v[12:13]
	v_mov_b32_e32 v14, v8
	v_add_f32_e32 v12, v12, v13
	v_mul_f32_e32 v13, 0x3b808081, v12
	v_fmac_f32_e32 v47, 0x3b808081, v12
	v_cndmask_b32_e64 v25, v13, v47, s[0:1]
	v_cvt_f32_ubyte0_e32 v13, v207
	v_cvt_f32_ubyte0_e32 v12, v205
	v_mov_b32_e32 v15, v48
	v_pk_mul_f32 v[12:13], v[14:15], v[12:13]
	v_mov_b32_e32 v48, v9
	v_add_f32_e32 v8, v12, v13
	v_mul_f32_e32 v12, 0x3b808081, v8
	v_fmac_f32_e32 v60, 0x3b808081, v8
	v_cndmask_b32_e64 v14, v12, v60, s[0:1]
	v_cvt_f32_ubyte1_e32 v13, v207
	v_cvt_f32_ubyte1_e32 v12, v205
	v_pk_mul_f32 v[8:9], v[48:49], v[12:13]
	v_mov_b32_e32 v12, v10
	v_add_f32_e32 v8, v8, v9
	v_mul_f32_e32 v9, 0x3b808081, v8
	v_fmac_f32_e32 v61, 0x3b808081, v8
	v_cndmask_b32_e64 v15, v9, v61, s[0:1]
	v_cvt_f32_ubyte2_e32 v9, v207
	v_cvt_f32_ubyte2_e32 v8, v205
	v_mov_b32_e32 v13, v50
	v_pk_mul_f32 v[8:9], v[12:13], v[8:9]
	v_mov_b32_e32 v50, v11
	v_add_f32_e32 v8, v8, v9
	v_mul_f32_e32 v9, 0x3b808081, v8
	v_fmac_f32_e32 v62, 0x3b808081, v8
	v_cndmask_b32_e64 v12, v9, v62, s[0:1]
	v_cvt_f32_ubyte3_e32 v9, v207
	v_cvt_f32_ubyte3_e32 v8, v205
	v_pk_mul_f32 v[8:9], v[50:51], v[8:9]
	v_cvt_pk_bf16_f32 v10, v14, v15
	v_add_f32_e32 v8, v8, v9
	v_mul_f32_e32 v9, 0x3b808081, v8
	v_fmac_f32_e32 v63, 0x3b808081, v8
	v_cndmask_b32_e64 v11, v9, v63, s[0:1]
	v_cvt_pk_bf16_f32 v8, v26, v27
	v_cvt_pk_bf16_f32 v9, v24, v25
	s_and_b64 vcc, exec, s[42:43]
	v_cvt_pk_bf16_f32 v11, v12, v11
	s_cbranch_vccnz .LBB0_893
	v_lshl_add_u64 v[12:13], s[10:11], 0, v[30:31]
	v_lshl_add_u64 v[12:13], v[152:153], 1, v[12:13]
	global_store_dwordx4 v[12:13], v[8:11], off
	s_cbranch_execnz .LBB0_881

.LBB0_881:
	s_nop 0
	s_nop 0
	v_cvt_f32_ubyte0_e32 v9, v228
	v_cvt_f32_ubyte0_e32 v8, v226
	v_mov_b32_e32 v10, v4
	v_mov_b32_e32 v11, v36
	v_pk_mul_f32 v[8:9], v[10:11], v[8:9]
	v_lshlrev_b32_e32 v12, 16, v246
	v_add_f32_e32 v4, v8, v9
	v_mul_f32_e32 v8, 0x3b808081, v4
	v_fmac_f32_e32 v12, 0x3b808081, v4
	v_cndmask_b32_e64 v10, v8, v12, s[0:1]
	v_cvt_f32_ubyte1_e32 v9, v228
	v_cvt_f32_ubyte1_e32 v8, v226
	v_mov_b32_e32 v36, v5
	v_pk_mul_f32 v[4:5], v[36:37], v[8:9]
	v_and_b32_e32 v13, 0xffff0000, v246
	v_add_f32_e32 v4, v4, v5
	v_mul_f32_e32 v5, 0x3b808081, v4
	v_fmac_f32_e32 v13, 0x3b808081, v4
	v_cndmask_b32_e64 v11, v5, v13, s[0:1]
	v_cvt_f32_ubyte2_e32 v5, v228
	v_cvt_f32_ubyte2_e32 v4, v226
	v_mov_b32_e32 v8, v6
	v_mov_b32_e32 v9, v38
	v_pk_mul_f32 v[4:5], v[8:9], v[4:5]
	v_lshlrev_b32_e32 v14, 16, v247
	v_add_f32_e32 v4, v4, v5
	v_mul_f32_e32 v5, 0x3b808081, v4
	v_fmac_f32_e32 v14, 0x3b808081, v4
	v_cndmask_b32_e64 v8, v5, v14, s[0:1]
	v_cvt_f32_ubyte3_e32 v5, v228
	v_cvt_f32_ubyte3_e32 v4, v226
	v_mov_b32_e32 v38, v7
	v_pk_mul_f32 v[4:5], v[38:39], v[4:5]
	v_and_b32_e32 v15, 0xffff0000, v247
	v_add_f32_e32 v4, v4, v5
	v_mul_f32_e32 v5, 0x3b808081, v4
	v_fmac_f32_e32 v15, 0x3b808081, v4
	v_cndmask_b32_e64 v9, v5, v15, s[0:1]
	v_cvt_f32_ubyte0_e32 v5, v229
	v_cvt_f32_ubyte0_e32 v4, v227
	v_mov_b32_e32 v6, v0
	v_mov_b32_e32 v7, v32
	v_pk_mul_f32 v[4:5], v[6:7], v[4:5]
	v_lshlrev_b32_e32 v16, 16, v248
	v_add_f32_e32 v0, v4, v5
	v_mul_f32_e32 v4, 0x3b808081, v0
	v_fmac_f32_e32 v16, 0x3b808081, v0
	v_cndmask_b32_e64 v6, v4, v16, s[0:1]
	v_cvt_f32_ubyte1_e32 v5, v229
	v_cvt_f32_ubyte1_e32 v4, v227
	v_mov_b32_e32 v32, v1
	v_pk_mul_f32 v[0:1], v[32:33], v[4:5]
	v_and_b32_e32 v17, 0xffff0000, v248
	v_add_f32_e32 v0, v0, v1
	v_mul_f32_e32 v1, 0x3b808081, v0
	v_fmac_f32_e32 v17, 0x3b808081, v0
	v_cndmask_b32_e64 v7, v1, v17, s[0:1]
	v_cvt_f32_ubyte2_e32 v1, v229
	v_cvt_f32_ubyte2_e32 v0, v227
	v_mov_b32_e32 v4, v2
	v_mov_b32_e32 v5, v34
	v_pk_mul_f32 v[0:1], v[4:5], v[0:1]
	v_lshlrev_b32_e32 v18, 16, v249
	v_add_f32_e32 v0, v0, v1
	v_mul_f32_e32 v1, 0x3b808081, v0
	v_fmac_f32_e32 v18, 0x3b808081, v0
	v_cndmask_b32_e64 v4, v1, v18, s[0:1]
	v_cvt_f32_ubyte3_e32 v1, v229
	v_cvt_f32_ubyte3_e32 v0, v227
	v_mov_b32_e32 v34, v3
	v_pk_mul_f32 v[0:1], v[34:35], v[0:1]
	v_and_b32_e32 v19, 0xffff0000, v249
	v_add_f32_e32 v0, v0, v1
	v_mul_f32_e32 v1, 0x3b808081, v0
	v_fmac_f32_e32 v19, 0x3b808081, v0
	v_cndmask_b32_e64 v3, v1, v19, s[0:1]
	v_cvt_pk_bf16_f32 v0, v10, v11
	v_cvt_pk_bf16_f32 v1, v8, v9
	v_cvt_pk_bf16_f32 v2, v6, v7
	s_and_b64 vcc, exec, s[42:43]
	v_cvt_pk_bf16_f32 v3, v4, v3
	s_cbranch_vccnz .LBB0_894
	v_lshl_add_u64 v[4:5], s[10:11], 0, v[22:23]
	v_lshl_add_u64 v[4:5], v[152:153], 1, v[4:5]
	global_store_dwordx4 v[4:5], v[0:3], off
	s_cbranch_execnz .LBB0_884
